# scan pass C pooling: the once-read U-row loads get the nt hint (like the other streamed scan inputs); on top of v49
# speedup vs baseline: 1.0133x; 1.0133x over previous
.LBB0_487:
	s_ashr_i32 s0, s18, 1
	s_lshl_b32 s1, s0, 6
	s_and_b32 s4, s22, 0xffffff00
	s_cmp_gt_i32 s0, 63
	s_cselect_b32 s25, 64, 0x100
	s_cselect_b32 s26, s1, s4
	s_and_b32 s0, s22, 32
	s_or_b32 s24, s1, s0
	s_add_i32 s27, s25, s26
	s_mov_b64 s[0:1], -1
	s_mov_b64 s[4:5], 0
	s_cmp_lt_i32 s20, 1
	s_mov_b64 s[6:7], 0
	s_cbranch_scc1 .LBB0_535
	s_cmp_gt_i32 s20, 1
	s_cbranch_scc0 .LBB0_504
	s_cmp_eq_u32 s20, 2
	s_mov_b64 s[6:7], -1
	s_cbranch_scc0 .LBB0_503
	s_add_i32 s13, s24, -4
	v_add_u32_e32 v1, s13, v99
	v_cmp_le_i32_e32 vcc, s26, v1
	v_cmp_gt_i32_e64 s[0:1], s27, v1
	s_and_b64 s[6:7], vcc, s[0:1]
	v_mov_b32_e32 v0, 0
	v_mov_b32_e32 v2, 0
	v_mov_b32_e32 v3, 0
	v_mov_b32_e32 v4, 0
	v_mov_b32_e32 v5, 0
	v_mov_b32_e32 v226, 0
	v_mov_b32_e32 v227, 0
	v_mov_b32_e32 v228, 0
	v_mov_b32_e32 v229, 0
	s_and_saveexec_b64 s[0:1], s[6:7]
	s_cbranch_execz .LBB0_492
	v_mad_i64_i32 v[226:227], s[6:7], v1, s53, v[6:7]
	global_load_dwordx4 v[226:229], v[226:227], off nt
.LBB0_492:
	s_or_b64 exec, exec, s[0:1]
	v_add_u32_e32 v4, s13, v118
	v_cmp_le_i32_e32 vcc, s26, v4
	v_cmp_gt_i32_e64 s[0:1], s27, v4
	s_and_b64 s[6:7], vcc, s[0:1]
	v_mov_b32_e32 v1, 0
	v_mov_b32_e32 v2, 0
	v_mov_b32_e32 v3, 0
	v_mov_b32_e32 v230, 0
	v_mov_b32_e32 v231, 0
	v_mov_b32_e32 v232, 0
	v_mov_b32_e32 v233, 0
	s_and_saveexec_b64 s[0:1], s[6:7]
	s_cbranch_execz .LBB0_494
	v_mad_i64_i32 v[230:231], s[6:7], v4, s53, v[6:7]
	global_load_dwordx4 v[230:233], v[230:231], off nt
.LBB0_494:
	s_or_b64 exec, exec, s[0:1]
	v_add_u32_e32 v1, s13, v119
	v_cmp_le_i32_e32 vcc, s26, v1
	v_cmp_gt_i32_e64 s[0:1], s27, v1
	s_and_b64 s[6:7], vcc, s[0:1]
	v_mov_b32_e32 v0, 0
	v_mov_b32_e32 v2, 0
	v_mov_b32_e32 v3, 0
	v_mov_b32_e32 v4, 0
	v_mov_b32_e32 v5, 0
	v_mov_b32_e32 v234, 0
	v_mov_b32_e32 v235, 0
	v_mov_b32_e32 v236, 0
	v_mov_b32_e32 v237, 0
	s_and_saveexec_b64 s[0:1], s[6:7]
	s_cbranch_execz .LBB0_496
	v_mad_i64_i32 v[234:235], s[6:7], v1, s53, v[6:7]
	global_load_dwordx4 v[234:237], v[234:235], off nt
.LBB0_496:
	s_or_b64 exec, exec, s[0:1]
	v_add_u32_e32 v4, s13, v120
	v_cmp_le_i32_e32 vcc, s26, v4
	v_cmp_gt_i32_e64 s[0:1], s27, v4
	s_and_b64 s[6:7], vcc, s[0:1]
	v_mov_b32_e32 v1, 0
	v_mov_b32_e32 v2, 0
	v_mov_b32_e32 v3, 0
	v_mov_b32_e32 v238, 0
	v_mov_b32_e32 v239, 0
	v_mov_b32_e32 v240, 0
	v_mov_b32_e32 v241, 0
	s_and_saveexec_b64 s[0:1], s[6:7]
	s_cbranch_execz .LBB0_498
	v_mad_i64_i32 v[238:239], s[6:7], v4, s53, v[6:7]
	global_load_dwordx4 v[238:241], v[238:239], off nt
.LBB0_498:
	s_or_b64 exec, exec, s[0:1]
	s_and_saveexec_b64 s[6:7], s[40:41]
	s_cbranch_execz .LBB0_502
	v_add_u32_e32 v5, s13, v121
	v_cmp_le_i32_e32 vcc, s26, v5
	v_cmp_gt_i32_e64 s[0:1], s27, v5
	s_and_b64 s[16:17], vcc, s[0:1]
	v_mov_b32_e32 v0, 0
	v_mov_b32_e32 v1, 0
	v_mov_b32_e32 v2, 0
	v_mov_b32_e32 v3, 0
	s_and_saveexec_b64 s[0:1], s[16:17]
	s_cbranch_execz .LBB0_501
	v_mad_i64_i32 v[0:1], s[16:17], v5, s53, v[6:7]
	global_load_dwordx4 v[0:3], v[0:1], off nt

.LBB0_504:
	s_and_b64 vcc, exec, s[0:1]
	s_cbranch_vccz .LBB0_518
	s_add_i32 s13, s24, -2
	v_add_u32_e32 v1, s13, v99
	v_cmp_le_i32_e32 vcc, s26, v1
	v_cmp_gt_i32_e64 s[0:1], s27, v1
	s_and_b64 s[16:17], vcc, s[0:1]
	v_mov_b32_e32 v0, 0
	v_mov_b32_e32 v2, 0
	v_mov_b32_e32 v3, 0
	v_mov_b32_e32 v4, 0
	v_mov_b32_e32 v5, 0
	v_mov_b32_e32 v226, 0
	v_mov_b32_e32 v227, 0
	v_mov_b32_e32 v228, 0
	v_mov_b32_e32 v229, 0
	s_and_saveexec_b64 s[0:1], s[16:17]
	s_cbranch_execz .LBB0_507
	v_mad_i64_i32 v[226:227], s[16:17], v1, s53, v[6:7]
	global_load_dwordx4 v[226:229], v[226:227], off nt
.LBB0_507:
	s_or_b64 exec, exec, s[0:1]
	v_add_u32_e32 v4, s13, v118
	v_cmp_le_i32_e32 vcc, s26, v4
	v_cmp_gt_i32_e64 s[0:1], s27, v4
	s_and_b64 s[16:17], vcc, s[0:1]
	v_mov_b32_e32 v1, 0
	v_mov_b32_e32 v2, 0
	v_mov_b32_e32 v3, 0
	v_mov_b32_e32 v230, 0
	v_mov_b32_e32 v231, 0
	v_mov_b32_e32 v232, 0
	v_mov_b32_e32 v233, 0
	s_and_saveexec_b64 s[0:1], s[16:17]
	s_cbranch_execz .LBB0_509
	v_mad_i64_i32 v[230:231], s[16:17], v4, s53, v[6:7]
	global_load_dwordx4 v[230:233], v[230:231], off nt
.LBB0_509:
	s_or_b64 exec, exec, s[0:1]
	v_add_u32_e32 v1, s13, v119
	v_cmp_le_i32_e32 vcc, s26, v1
	v_cmp_gt_i32_e64 s[0:1], s27, v1
	s_and_b64 s[16:17], vcc, s[0:1]
	v_mov_b32_e32 v0, 0
	v_mov_b32_e32 v2, 0
	v_mov_b32_e32 v3, 0
	v_mov_b32_e32 v4, 0
	v_mov_b32_e32 v5, 0
	v_mov_b32_e32 v234, 0
	v_mov_b32_e32 v235, 0
	v_mov_b32_e32 v236, 0
	v_mov_b32_e32 v237, 0
	s_and_saveexec_b64 s[0:1], s[16:17]
	s_cbranch_execz .LBB0_511
	v_mad_i64_i32 v[234:235], s[16:17], v1, s53, v[6:7]
	global_load_dwordx4 v[234:237], v[234:235], off nt
.LBB0_511:
	s_or_b64 exec, exec, s[0:1]
	v_add_u32_e32 v4, s13, v120
	v_cmp_le_i32_e32 vcc, s26, v4
	v_cmp_gt_i32_e64 s[0:1], s27, v4
	s_and_b64 s[16:17], vcc, s[0:1]
	v_mov_b32_e32 v1, 0
	v_mov_b32_e32 v2, 0
	v_mov_b32_e32 v3, 0
	v_mov_b32_e32 v238, 0
	v_mov_b32_e32 v239, 0
	v_mov_b32_e32 v240, 0
	v_mov_b32_e32 v241, 0
	s_and_saveexec_b64 s[0:1], s[16:17]
	s_cbranch_execz .LBB0_513
	v_mad_i64_i32 v[238:239], s[16:17], v4, s53, v[6:7]
	global_load_dwordx4 v[238:241], v[238:239], off nt
.LBB0_513:
	s_or_b64 exec, exec, s[0:1]
	s_and_saveexec_b64 s[16:17], s[42:43]
	s_cbranch_execz .LBB0_517
	v_add_u32_e32 v5, s13, v121
	v_cmp_le_i32_e32 vcc, s26, v5
	v_cmp_gt_i32_e64 s[0:1], s27, v5
	s_and_b64 s[28:29], vcc, s[0:1]
	v_mov_b32_e32 v0, 0
	v_mov_b32_e32 v1, 0
	v_mov_b32_e32 v2, 0
	v_mov_b32_e32 v3, 0
	s_and_saveexec_b64 s[0:1], s[28:29]
	s_cbranch_execz .LBB0_516
	v_mad_i64_i32 v[0:1], s[28:29], v5, s53, v[6:7]
	global_load_dwordx4 v[0:3], v[0:1], off nt

.LBB0_520:
	s_add_i32 s6, s24, -8
	v_or_b32_e32 v1, s6, v99
	v_cmp_le_i32_e32 vcc, s26, v1
	v_cmp_gt_i32_e64 s[0:1], s27, v1
	s_and_b64 s[4:5], vcc, s[0:1]
	v_mov_b32_e32 v0, 0
	v_mov_b32_e32 v2, 0
	v_mov_b32_e32 v3, 0
	v_mov_b32_e32 v4, 0
	v_mov_b32_e32 v5, 0
	v_mov_b32_e32 v226, 0
	v_mov_b32_e32 v227, 0
	v_mov_b32_e32 v228, 0
	v_mov_b32_e32 v229, 0
	s_and_saveexec_b64 s[0:1], s[4:5]
	s_cbranch_execz .LBB0_522
	v_mad_i64_i32 v[226:227], s[4:5], v1, s53, v[6:7]
	global_load_dwordx4 v[226:229], v[226:227], off nt
.LBB0_522:
	s_or_b64 exec, exec, s[0:1]
	v_add_u32_e32 v4, s6, v118
	v_cmp_le_i32_e32 vcc, s26, v4
	v_cmp_gt_i32_e64 s[0:1], s27, v4
	s_and_b64 s[4:5], vcc, s[0:1]
	v_mov_b32_e32 v1, 0
	v_mov_b32_e32 v2, 0
	v_mov_b32_e32 v3, 0
	v_mov_b32_e32 v230, 0
	v_mov_b32_e32 v231, 0
	v_mov_b32_e32 v232, 0
	v_mov_b32_e32 v233, 0
	s_and_saveexec_b64 s[0:1], s[4:5]
	s_cbranch_execz .LBB0_524
	v_mad_i64_i32 v[230:231], s[4:5], v4, s53, v[6:7]
	global_load_dwordx4 v[230:233], v[230:231], off nt
.LBB0_524:
	s_or_b64 exec, exec, s[0:1]
	v_add_u32_e32 v1, s6, v119
	v_cmp_le_i32_e32 vcc, s26, v1
	v_cmp_gt_i32_e64 s[0:1], s27, v1
	s_and_b64 s[4:5], vcc, s[0:1]
	v_mov_b32_e32 v0, 0
	v_mov_b32_e32 v2, 0
	v_mov_b32_e32 v3, 0
	v_mov_b32_e32 v4, 0
	v_mov_b32_e32 v5, 0
	v_mov_b32_e32 v234, 0
	v_mov_b32_e32 v235, 0
	v_mov_b32_e32 v236, 0
	v_mov_b32_e32 v237, 0
	s_and_saveexec_b64 s[0:1], s[4:5]
	s_cbranch_execz .LBB0_526
	v_mad_i64_i32 v[234:235], s[4:5], v1, s53, v[6:7]
	global_load_dwordx4 v[234:237], v[234:235], off nt
.LBB0_526:
	s_or_b64 exec, exec, s[0:1]
	v_add_u32_e32 v4, s6, v120
	v_cmp_le_i32_e32 vcc, s26, v4
	v_cmp_gt_i32_e64 s[0:1], s27, v4
	s_and_b64 s[4:5], vcc, s[0:1]
	v_mov_b32_e32 v1, 0
	v_mov_b32_e32 v2, 0
	v_mov_b32_e32 v3, 0
	v_mov_b32_e32 v238, 0
	v_mov_b32_e32 v239, 0
	v_mov_b32_e32 v240, 0
	v_mov_b32_e32 v241, 0
	s_and_saveexec_b64 s[0:1], s[4:5]
	s_cbranch_execz .LBB0_528
	v_mad_i64_i32 v[238:239], s[4:5], v4, s53, v[6:7]
	global_load_dwordx4 v[238:241], v[238:239], off nt
.LBB0_528:
	s_or_b64 exec, exec, s[0:1]
	v_add_u32_e32 v5, s6, v121
	v_cmp_le_i32_e32 vcc, s26, v5
	v_cmp_gt_i32_e64 s[0:1], s27, v5
	s_and_b64 s[4:5], vcc, s[0:1]
	v_mov_b32_e32 v0, 0
	v_mov_b32_e32 v1, 0
	v_mov_b32_e32 v2, 0
	v_mov_b32_e32 v3, 0
	v_mov_b32_e32 v242, 0
	v_mov_b32_e32 v243, 0
	v_mov_b32_e32 v244, 0
	v_mov_b32_e32 v245, 0
	s_and_saveexec_b64 s[0:1], s[4:5]
	s_cbranch_execz .LBB0_530
	v_mad_i64_i32 v[242:243], s[4:5], v5, s53, v[6:7]
	global_load_dwordx4 v[242:245], v[242:243], off nt
.LBB0_530:
	s_or_b64 exec, exec, s[0:1]
	s_and_saveexec_b64 s[4:5], s[40:41]
	s_cbranch_execz .LBB0_534
	v_add_u32_e32 v5, s6, v122
	v_cmp_le_i32_e32 vcc, s26, v5
	v_cmp_gt_i32_e64 s[0:1], s27, v5
	s_and_b64 s[6:7], vcc, s[0:1]
	v_mov_b32_e32 v0, 0
	v_mov_b32_e32 v1, 0
	v_mov_b32_e32 v2, 0
	v_mov_b32_e32 v3, 0
	s_and_saveexec_b64 s[0:1], s[6:7]
	s_cbranch_execz .LBB0_533
	v_mad_i64_i32 v[0:1], s[6:7], v5, s53, v[6:7]
	global_load_dwordx4 v[0:3], v[0:1], off nt

.LBB0_537:
	s_and_b64 vcc, exec, s[4:5]
	s_cbranch_vccz .LBB0_486
	s_add_i32 s4, s24, -1
	v_add_u32_e32 v1, s4, v99
	v_cmp_le_i32_e32 vcc, s26, v1
	v_cmp_gt_i32_e64 s[0:1], s27, v1
	s_and_b64 s[6:7], vcc, s[0:1]
	v_mov_b32_e32 v0, 0
	v_mov_b32_e32 v2, 0
	v_mov_b32_e32 v3, 0
	v_mov_b32_e32 v4, 0
	v_mov_b32_e32 v5, 0
	v_mov_b32_e32 v226, 0
	v_mov_b32_e32 v227, 0
	v_mov_b32_e32 v228, 0
	v_mov_b32_e32 v229, 0
	s_and_saveexec_b64 s[0:1], s[6:7]
	s_cbranch_execz .LBB0_540
	v_mad_i64_i32 v[226:227], s[6:7], v1, s53, v[6:7]
	global_load_dwordx4 v[226:229], v[226:227], off nt
.LBB0_540:
	s_or_b64 exec, exec, s[0:1]
	v_add_u32_e32 v4, s4, v118
	v_cmp_le_i32_e32 vcc, s26, v4
	v_cmp_gt_i32_e64 s[0:1], s27, v4
	s_and_b64 s[6:7], vcc, s[0:1]
	v_mov_b32_e32 v1, 0
	v_mov_b32_e32 v2, 0
	v_mov_b32_e32 v3, 0
	v_mov_b32_e32 v230, 0
	v_mov_b32_e32 v231, 0
	v_mov_b32_e32 v232, 0
	v_mov_b32_e32 v233, 0
	s_and_saveexec_b64 s[0:1], s[6:7]
	s_cbranch_execz .LBB0_542
	v_mad_i64_i32 v[230:231], s[6:7], v4, s53, v[6:7]
	global_load_dwordx4 v[230:233], v[230:231], off nt
.LBB0_542:
	s_or_b64 exec, exec, s[0:1]
	v_add_u32_e32 v1, s4, v119
	v_cmp_le_i32_e32 vcc, s26, v1
	v_cmp_gt_i32_e64 s[0:1], s27, v1
	s_and_b64 s[6:7], vcc, s[0:1]
	v_mov_b32_e32 v0, 0
	v_mov_b32_e32 v2, 0
	v_mov_b32_e32 v3, 0
	v_mov_b32_e32 v4, 0
	v_mov_b32_e32 v5, 0
	v_mov_b32_e32 v234, 0
	v_mov_b32_e32 v235, 0
	v_mov_b32_e32 v236, 0
	v_mov_b32_e32 v237, 0
	s_and_saveexec_b64 s[0:1], s[6:7]
	s_cbranch_execz .LBB0_544
	v_mad_i64_i32 v[234:235], s[6:7], v1, s53, v[6:7]
	global_load_dwordx4 v[234:237], v[234:235], off nt
.LBB0_544:
	s_or_b64 exec, exec, s[0:1]
	v_add_u32_e32 v4, s4, v120
	v_cmp_le_i32_e32 vcc, s26, v4
	v_cmp_gt_i32_e64 s[0:1], s27, v4
	s_and_b64 s[4:5], vcc, s[0:1]
	v_mov_b32_e32 v1, 0
	v_mov_b32_e32 v2, 0
	v_mov_b32_e32 v3, 0
	v_mov_b32_e32 v238, 0
	v_mov_b32_e32 v239, 0
	v_mov_b32_e32 v240, 0
	v_mov_b32_e32 v241, 0
	s_and_saveexec_b64 s[0:1], s[4:5]
	s_cbranch_execz .LBB0_546
	v_mad_i64_i32 v[238:239], s[4:5], v4, s53, v[6:7]
	global_load_dwordx4 v[238:241], v[238:239], off nt
.LBB0_546:
	s_or_b64 exec, exec, s[0:1]
	s_and_saveexec_b64 s[0:1], s[44:45]
	s_cbranch_execz .LBB0_485
	s_or_b32 s4, s24, 31
	s_cmp_ge_i32 s4, s26
	s_cselect_b64 s[6:7], -1, 0
	s_cmp_lt_i32 s4, s27
	s_cselect_b64 s[16:17], -1, 0
	s_and_b64 s[6:7], s[6:7], s[16:17]
	v_mov_b32_e32 v0, 0
	s_andn2_b64 vcc, exec, s[6:7]
	v_mov_b32_e32 v1, 0
	v_mov_b32_e32 v2, 0
	v_mov_b32_e32 v3, 0
	s_cbranch_vccnz .LBB0_484
	v_mad_i64_i32 v[0:1], s[4:5], s4, v208, v[6:7]
	global_load_dwordx4 v[0:3], v[0:1], off nt
	s_branch .LBB0_484
